# diff-attention epilogue: xor-butterfly hops 1,2,4,8 of the subln row sums done with DPP moves instead of ds_swizzle LDS round trips; lgkmcnt waits of that region re-derived
# speedup vs baseline: 1.0018x; 1.0010x over previous
.LBB0_1369:
	s_waitcnt lgkmcnt(0)
	s_barrier
	s_andn2_b64 vcc, exec, s[62:63]
	s_cbranch_vccnz .LBB0_1371
	v_readlane_b32 s4, v255, 14
	v_readlane_b32 s5, v255, 15
	s_nop 4
	global_load_dword v29, v15, s[4:5]
	global_load_dword v43, v15, s[4:5] offset:128
	global_load_dword v48, v15, s[4:5] offset:256
	global_load_dword v49, v15, s[4:5] offset:384
	s_lshl_b32 s1, s0, 13
	s_lshl_b32 s0, s0, 14
	s_add_i32 s1, s1, 0
	s_add_i32 s4, s0, 0
	v_lshlrev_b32_e32 v16, 10, v94
	v_lshlrev_b32_e32 v17, 1, v95
	s_add_i32 s0, s1, 0x10000
	v_add3_u32 v15, s4, v6, v15
	v_add3_u32 v6, s0, v16, v17
	ds_read2_b32 v[16:17], v15 offset1:32
	ds_read2_b32 v[22:23], v15 offset0:64 offset1:96
	ds_read2_b32 v[30:31], v15 offset0:128 offset1:160
	ds_read2_b32 v[32:33], v15 offset0:192 offset1:224
	v_add_u32_e32 v57, 0x400, v15
	s_waitcnt lgkmcnt(3)
	v_sub_f32_e32 v17, v85, v17
	v_sub_f32_e32 v16, v83, v16
	v_mul_f32_e32 v58, v17, v17
	s_waitcnt lgkmcnt(2)
	v_sub_f32_e32 v22, v86, v22
	v_fmac_f32_e32 v58, v16, v16
	v_sub_f32_e32 v23, v87, v23
	v_fmac_f32_e32 v58, v22, v22
	v_fmac_f32_e32 v58, v23, v23
	s_nop 1
	v_mov_b32_dpp v59, v58 quad_perm:[1,0,3,2] row_mask:0xf bank_mask:0xf
	s_waitcnt lgkmcnt(1)
	v_sub_f32_e32 v31, v92, v31
	v_sub_f32_e32 v30, v90, v30
	v_mul_f32_e32 v60, v31, v31
	s_waitcnt lgkmcnt(0)
	v_sub_f32_e32 v32, v93, v32
	v_add_f32_e32 v58, v58, v59
	s_nop 1
	v_mov_b32_dpp v59, v58 quad_perm:[2,3,0,1] row_mask:0xf bank_mask:0xf
	v_fmac_f32_e32 v60, v30, v30
	v_sub_f32_e32 v33, v88, v33
	v_fmac_f32_e32 v60, v32, v32
	v_fmac_f32_e32 v60, v33, v33
	v_add_f32_e32 v58, v58, v59
	s_nop 0
	v_mov_b32_dpp v61, v60 quad_perm:[1,0,3,2] row_mask:0xf bank_mask:0xf
	v_mov_b32_dpp v59, v58 row_half_mirror row_mask:0xf bank_mask:0xf
	ds_read2_b32 v[44:45], v57 offset1:32
	ds_read2_b32 v[46:47], v57 offset0:64 offset1:96
	s_lshl_b64 s[4:5], s[60:61], 11
	s_add_u32 s1, s91, s4
	v_add_f32_e32 v60, v60, v61
	v_add_f32_e32 v58, v58, v59
	s_nop 0
	v_mov_b32_dpp v61, v60 quad_perm:[2,3,0,1] row_mask:0xf bank_mask:0xf
	v_mov_b32_dpp v59, v58 row_mirror row_mask:0xf bank_mask:0xf
	s_waitcnt lgkmcnt(1)
	v_sub_f32_e32 v45, v91, v45
	v_sub_f32_e32 v44, v89, v44
	v_mul_f32_e32 v62, v45, v45
	v_add_f32_e32 v60, v60, v61
	v_add_f32_e32 v58, v58, v59
	s_nop 0
	v_mov_b32_dpp v61, v60 row_half_mirror row_mask:0xf bank_mask:0xf
	ds_swizzle_b32 v59, v58 offset:swizzle(SWAP,16)
	s_waitcnt lgkmcnt(1)
	v_sub_f32_e32 v46, v84, v46
	v_fmac_f32_e32 v62, v44, v44
	v_sub_f32_e32 v47, v82, v47
	v_add_f32_e32 v60, v60, v61
	s_waitcnt lgkmcnt(0)
	v_add_f32_e32 v58, v58, v59
	v_mov_b32_dpp v61, v60 row_mirror row_mask:0xf bank_mask:0xf
	v_fmamk_f32 v58, v58, 0x3c000000, v244
	v_fmac_f32_e32 v62, v46, v46
	v_rsq_f32_e32 v58, v58
	v_fmac_f32_e32 v62, v47, v47
	s_nop 1
	v_mov_b32_dpp v59, v62 quad_perm:[1,0,3,2] row_mask:0xf bank_mask:0xf
	v_add_f32_e32 v60, v60, v61
	v_mul_f32_e32 v63, v16, v58
	v_mul_f32_e32 v64, v17, v58
	v_mul_f32_e32 v65, v22, v58
	v_mul_f32_e32 v58, v23, v58
	ds_swizzle_b32 v61, v60 offset:swizzle(SWAP,16)
	s_addc_u32 s5, s95, s5
	s_add_u32 s4, s1, s8
	s_addc_u32 s5, s5, 0
	s_waitcnt vmcnt(3)
	v_mul_f32_e32 v23, 0x3f4ccccd, v29
	s_waitcnt vmcnt(2)
	v_mul_f32_e32 v22, 0x3f4ccccd, v43
	s_waitcnt vmcnt(1)
	v_mul_f32_e32 v17, 0x3f4ccccd, v48
	v_mul_f32_e32 v29, v23, v63
	v_mul_f32_e32 v43, v22, v64
	v_mul_f32_e32 v48, v17, v65
	v_cvt_pk_bf16_f32 v29, v29, s0
	v_cvt_pk_bf16_f32 v43, v43, s0
	v_cvt_pk_bf16_f32 v48, v48, s0
	ds_write_b16 v6, v29
	ds_write_b16 v6, v43 offset:64
	ds_write_b16 v6, v48 offset:128
	v_add_f32_e32 v43, v62, v59
	s_nop 1
	v_mov_b32_dpp v48, v43 quad_perm:[2,3,0,1] row_mask:0xf bank_mask:0xf
	s_waitcnt lgkmcnt(3)
	v_add_f32_e32 v29, v60, v61
	v_fmamk_f32 v29, v29, 0x3c000000, v244
	v_rsq_f32_e32 v29, v29
	s_waitcnt vmcnt(0)
	v_mul_f32_e32 v16, 0x3f4ccccd, v49
	v_add_f32_e32 v43, v43, v48
	s_nop 1
	v_mov_b32_dpp v48, v43 row_half_mirror row_mask:0xf bank_mask:0xf
	v_mul_f32_e32 v30, v30, v29
	v_mul_f32_e32 v30, v23, v30
	v_cvt_pk_bf16_f32 v30, v30, s0
	ds_write_b16 v6, v30 offset:256
	v_mul_f32_e32 v30, v31, v29
	v_add_f32_e32 v31, v43, v48
	s_nop 1
	v_mov_b32_dpp v43, v31 row_mirror row_mask:0xf bank_mask:0xf
	v_mul_f32_e32 v30, v22, v30
	v_cvt_pk_bf16_f32 v30, v30, s0
	ds_write_b16 v6, v30 offset:320
	v_mul_f32_e32 v30, v32, v29
	v_add_f32_e32 v31, v31, v43
	ds_swizzle_b32 v32, v31 offset:swizzle(SWAP,16)
	v_mul_f32_e32 v30, v17, v30
	v_cvt_pk_bf16_f32 v30, v30, s0
	ds_write_b16 v6, v30 offset:384
	v_mul_f32_e32 v29, v33, v29
	s_waitcnt lgkmcnt(1)
	v_add_f32_e32 v30, v31, v32
	v_fmamk_f32 v30, v30, 0x3c000000, v244
	v_rsq_f32_e32 v43, v30
	ds_read2_b32 v[30:31], v57 offset0:128 offset1:160
	ds_read2_b32 v[32:33], v57 offset0:192 offset1:224
	v_mul_f32_e32 v29, v16, v29
	v_mul_f32_e32 v49, v16, v58
	v_cvt_pk_bf16_f32 v29, v29, s0
	s_waitcnt lgkmcnt(1)
	v_sub_f32_e32 v48, v81, v31
	v_cvt_pk_bf16_f32 v49, v49, s0
	ds_write_b16 v6, v29 offset:448
	v_mul_f32_e32 v29, v44, v43
	v_sub_f32_e32 v44, v78, v30
	v_mul_f32_e32 v30, v48, v48
	ds_write_b16 v6, v49 offset:192
	v_fmac_f32_e32 v30, v44, v44
	s_waitcnt lgkmcnt(2)
	v_sub_f32_e32 v49, v80, v32
	v_fmac_f32_e32 v30, v49, v49
	v_sub_f32_e32 v57, v79, v33
	v_fmac_f32_e32 v30, v57, v57
	s_nop 1
	v_mov_b32_dpp v31, v30 quad_perm:[1,0,3,2] row_mask:0xf bank_mask:0xf
	v_mul_f32_e32 v29, v23, v29
	v_cvt_pk_bf16_f32 v29, v29, s0
	ds_write_b16 v6, v29 offset:512
	v_mul_f32_e32 v29, v45, v43
	v_add_f32_e32 v30, v30, v31
	s_nop 1
	v_mov_b32_dpp v31, v30 quad_perm:[2,3,0,1] row_mask:0xf bank_mask:0xf
	v_mul_f32_e32 v29, v22, v29
	v_cvt_pk_bf16_f32 v29, v29, s0
	ds_write_b16 v6, v29 offset:576
	v_mul_f32_e32 v29, v46, v43
	v_add_f32_e32 v30, v30, v31
	s_nop 1
	v_mov_b32_dpp v31, v30 row_half_mirror row_mask:0xf bank_mask:0xf
	v_mul_f32_e32 v29, v17, v29
	v_cvt_pk_bf16_f32 v29, v29, s0
	ds_write_b16 v6, v29 offset:640
	v_mul_f32_e32 v29, v47, v43
	v_add_f32_e32 v32, v30, v31
	s_nop 1
	v_mov_b32_dpp v33, v32 row_mirror row_mask:0xf bank_mask:0xf
	v_add_u32_e32 v43, 0x1000, v15
	ds_read2_b32 v[30:31], v43 offset1:32
	v_mul_f32_e32 v29, v16, v29
	v_cvt_pk_bf16_f32 v29, v29, s0
	v_add_f32_e32 v45, v32, v33
	ds_read2_b32 v[32:33], v43 offset0:64 offset1:96
	s_waitcnt lgkmcnt(1)
	v_sub_f32_e32 v58, v77, v31
	v_sub_f32_e32 v47, v74, v30
	v_mul_f32_e32 v30, v58, v58
	v_fmac_f32_e32 v30, v47, v47
	s_waitcnt lgkmcnt(0)
	v_sub_f32_e32 v59, v76, v32
	v_fmac_f32_e32 v30, v59, v59
	v_sub_f32_e32 v60, v75, v33
	v_fmac_f32_e32 v30, v60, v60
	s_nop 1
	v_mov_b32_dpp v31, v30 quad_perm:[1,0,3,2] row_mask:0xf bank_mask:0xf
	ds_write_b16 v6, v29 offset:704
	ds_swizzle_b32 v46, v45 offset:swizzle(SWAP,16)
	v_add_f32_e32 v29, v30, v31
	s_nop 1
	v_mov_b32_dpp v30, v29 quad_perm:[2,3,0,1] row_mask:0xf bank_mask:0xf
	s_waitcnt lgkmcnt(0)
	v_add_f32_e32 v32, v45, v46
	v_fmamk_f32 v32, v32, 0x3c000000, v244
	v_rsq_f32_e32 v32, v32
	v_add_f32_e32 v29, v29, v30
	s_nop 1
	v_mov_b32_dpp v30, v29 row_half_mirror row_mask:0xf bank_mask:0xf
	v_mul_f32_e32 v31, v44, v32
	v_mul_f32_e32 v31, v23, v31
	v_cvt_pk_bf16_f32 v31, v31, s0
	ds_write_b16 v6, v31 offset:768
	v_add_f32_e32 v29, v29, v30
	s_nop 1
	v_mov_b32_dpp v30, v29 row_mirror row_mask:0xf bank_mask:0xf
	v_mul_f32_e32 v31, v48, v32
	v_mul_f32_e32 v31, v22, v31
	v_cvt_pk_bf16_f32 v31, v31, s0
	ds_write_b16 v6, v31 offset:832
	v_add_f32_e32 v29, v29, v30
	v_mul_f32_e32 v31, v49, v32
	ds_swizzle_b32 v33, v29 offset:swizzle(SWAP,16)
	v_mul_f32_e32 v31, v17, v31
	v_mul_f32_e32 v30, v57, v32
	v_cvt_pk_bf16_f32 v31, v31, s0
	v_mul_f32_e32 v30, v16, v30
	ds_write_b16 v6, v31 offset:896
	v_cvt_pk_bf16_f32 v44, v30, s0
	ds_read2_b32 v[30:31], v43 offset0:128 offset1:160
	s_waitcnt lgkmcnt(2)
	v_add_f32_e32 v29, v29, v33
	ds_read2_b32 v[32:33], v43 offset0:192 offset1:224
	v_fmamk_f32 v29, v29, 0x3c000000, v244
	v_rsq_f32_e32 v29, v29
	s_waitcnt lgkmcnt(1)
	v_sub_f32_e32 v45, v73, v31
	v_sub_f32_e32 v43, v70, v30
	v_mul_f32_e32 v30, v45, v45
	v_fmac_f32_e32 v30, v43, v43
	s_waitcnt lgkmcnt(0)
	v_sub_f32_e32 v46, v72, v32
	v_fmac_f32_e32 v30, v46, v46
	v_sub_f32_e32 v48, v71, v33
	v_fmac_f32_e32 v30, v48, v48
	s_nop 1
	v_mov_b32_dpp v31, v30 quad_perm:[1,0,3,2] row_mask:0xf bank_mask:0xf
	v_mul_f32_e32 v32, v47, v29
	v_mul_f32_e32 v32, v23, v32
	v_cvt_pk_bf16_f32 v32, v32, s0
	ds_write_b16 v6, v32 offset:2048
	v_add_f32_e32 v30, v30, v31
	s_nop 1
	v_mov_b32_dpp v31, v30 quad_perm:[2,3,0,1] row_mask:0xf bank_mask:0xf
	v_mul_f32_e32 v32, v58, v29
	ds_write_b16 v6, v44 offset:960
	v_mul_f32_e32 v32, v22, v32
	v_cvt_pk_bf16_f32 v32, v32, s0
	v_add_f32_e32 v30, v30, v31
	s_nop 1
	v_mov_b32_dpp v31, v30 row_half_mirror row_mask:0xf bank_mask:0xf
	ds_write_b16 v6, v32 offset:2112
	v_mul_f32_e32 v32, v59, v29
	v_add_u32_e32 v47, 0x1400, v15
	v_mul_f32_e32 v32, v17, v32
	v_add_f32_e32 v33, v30, v31
	s_nop 1
	v_mov_b32_dpp v44, v33 row_mirror row_mask:0xf bank_mask:0xf
	ds_read2_b32 v[30:31], v47 offset1:32
	v_cvt_pk_bf16_f32 v32, v32, s0
	ds_write_b16 v6, v32 offset:2176
	v_mul_f32_e32 v29, v60, v29
	v_add_f32_e32 v44, v33, v44
	ds_read2_b32 v[32:33], v47 offset0:64 offset1:96
	s_waitcnt lgkmcnt(2)
	v_sub_f32_e32 v56, v56, v31
	v_sub_f32_e32 v57, v67, v30
	v_mul_f32_e32 v30, v56, v56
	v_fmac_f32_e32 v30, v57, v57
	s_waitcnt lgkmcnt(0)
	v_sub_f32_e32 v58, v68, v32
	v_fmac_f32_e32 v30, v58, v58
	v_sub_f32_e32 v59, v69, v33
	v_fmac_f32_e32 v30, v59, v59
	s_nop 1
	v_mov_b32_dpp v31, v30 quad_perm:[1,0,3,2] row_mask:0xf bank_mask:0xf
	ds_swizzle_b32 v49, v44 offset:swizzle(SWAP,16)
	v_mul_f32_e32 v29, v16, v29
	v_cvt_pk_bf16_f32 v29, v29, s0
	ds_write_b16 v6, v29 offset:2240
	v_add_f32_e32 v30, v30, v31
	s_nop 1
	v_mov_b32_dpp v31, v30 quad_perm:[2,3,0,1] row_mask:0xf bank_mask:0xf
	s_waitcnt lgkmcnt(1)
	v_add_f32_e32 v32, v44, v49
	v_fmamk_f32 v32, v32, 0x3c000000, v244
	v_rsq_f32_e32 v32, v32
	v_add_f32_e32 v30, v30, v31
	s_nop 1
	v_mov_b32_dpp v31, v30 row_half_mirror row_mask:0xf bank_mask:0xf
	v_mul_f32_e32 v29, v43, v32
	v_mul_f32_e32 v29, v23, v29
	v_cvt_pk_bf16_f32 v29, v29, s0
	ds_write_b16 v6, v29 offset:2304
	v_add_f32_e32 v30, v30, v31
	s_nop 1
	v_mov_b32_dpp v31, v30 row_mirror row_mask:0xf bank_mask:0xf
	v_mul_f32_e32 v29, v45, v32
	v_mul_f32_e32 v29, v22, v29
	v_cvt_pk_bf16_f32 v29, v29, s0
	ds_write_b16 v6, v29 offset:2368
	v_add_f32_e32 v30, v30, v31
	ds_swizzle_b32 v31, v30 offset:swizzle(SWAP,16)
	v_mul_f32_e32 v29, v46, v32
	v_mul_f32_e32 v29, v17, v29
	v_cvt_pk_bf16_f32 v29, v29, s0
	ds_write_b16 v6, v29 offset:2432
	s_waitcnt lgkmcnt(1)
	v_add_f32_e32 v30, v30, v31
	v_fmamk_f32 v30, v30, 0x3c000000, v244
	v_rsq_f32_e32 v43, v30
	ds_read2_b32 v[30:31], v47 offset0:128 offset1:160
	v_mul_f32_e32 v29, v48, v32
	ds_read2_b32 v[32:33], v47 offset0:192 offset1:224
	v_mul_f32_e32 v29, v16, v29
	v_cvt_pk_bf16_f32 v29, v29, s0
	s_waitcnt lgkmcnt(1)
	v_sub_f32_e32 v45, v55, v31
	v_sub_f32_e32 v44, v52, v30
	v_mul_f32_e32 v30, v45, v45
	v_fmac_f32_e32 v30, v44, v44
	s_waitcnt lgkmcnt(0)
	v_sub_f32_e32 v46, v54, v32
	v_fmac_f32_e32 v30, v46, v46
	v_sub_f32_e32 v47, v53, v33
	v_fmac_f32_e32 v30, v47, v47
	s_nop 1
	v_mov_b32_dpp v31, v30 quad_perm:[1,0,3,2] row_mask:0xf bank_mask:0xf
	ds_write_b16 v6, v29 offset:2496
	v_mul_f32_e32 v29, v57, v43
	v_mul_f32_e32 v29, v23, v29
	v_cvt_pk_bf16_f32 v29, v29, s0
	v_add_f32_e32 v30, v30, v31
	s_nop 1
	v_mov_b32_dpp v31, v30 quad_perm:[2,3,0,1] row_mask:0xf bank_mask:0xf
	ds_write_b16 v6, v29 offset:2560
	v_mul_f32_e32 v29, v56, v43
	v_mul_f32_e32 v29, v22, v29
	v_cvt_pk_bf16_f32 v29, v29, s0
	v_add_f32_e32 v30, v30, v31
	s_nop 1
	v_mov_b32_dpp v31, v30 row_half_mirror row_mask:0xf bank_mask:0xf
	ds_write_b16 v6, v29 offset:2624
	v_mul_f32_e32 v29, v58, v43
	v_mul_f32_e32 v29, v17, v29
	v_cvt_pk_bf16_f32 v29, v29, s0
	v_add_f32_e32 v32, v30, v31
	s_nop 1
	v_mov_b32_dpp v33, v32 row_mirror row_mask:0xf bank_mask:0xf
	ds_write_b16 v6, v29 offset:2688
	v_mul_f32_e32 v29, v59, v43
	v_add_u32_e32 v43, 0x2000, v15
	ds_read2_b32 v[30:31], v43 offset1:32
	v_add_f32_e32 v48, v32, v33
	ds_read2_b32 v[32:33], v43 offset0:64 offset1:96
	v_mul_f32_e32 v29, v16, v29
	v_cvt_pk_bf16_f32 v29, v29, s0
	s_waitcnt lgkmcnt(1)
	v_sub_f32_e32 v51, v51, v31
	v_sub_f32_e32 v50, v50, v30
	v_mul_f32_e32 v30, v51, v51
	v_fmac_f32_e32 v30, v50, v50
	s_waitcnt lgkmcnt(0)
	v_sub_f32_e32 v42, v42, v32
	v_fmac_f32_e32 v30, v42, v42
	v_sub_f32_e32 v41, v41, v33
	v_fmac_f32_e32 v30, v41, v41
	s_nop 1
	v_mov_b32_dpp v31, v30 quad_perm:[1,0,3,2] row_mask:0xf bank_mask:0xf
	ds_write_b16 v6, v29 offset:2752
	ds_swizzle_b32 v49, v48 offset:swizzle(SWAP,16)
	v_add_f32_e32 v29, v30, v31
	s_nop 1
	v_mov_b32_dpp v30, v29 quad_perm:[2,3,0,1] row_mask:0xf bank_mask:0xf
	s_waitcnt lgkmcnt(0)
	v_add_f32_e32 v32, v48, v49
	v_fmamk_f32 v32, v32, 0x3c000000, v244
	v_rsq_f32_e32 v32, v32
	v_add_f32_e32 v29, v29, v30
	s_nop 1
	v_mov_b32_dpp v30, v29 row_half_mirror row_mask:0xf bank_mask:0xf
	v_mul_f32_e32 v31, v44, v32
	v_mul_f32_e32 v31, v23, v31
	v_cvt_pk_bf16_f32 v31, v31, s0
	ds_write_b16 v6, v31 offset:2816
	v_add_f32_e32 v29, v29, v30
	s_nop 1
	v_mov_b32_dpp v30, v29 row_mirror row_mask:0xf bank_mask:0xf
	v_mul_f32_e32 v31, v45, v32
	v_mul_f32_e32 v31, v22, v31
	v_cvt_pk_bf16_f32 v31, v31, s0
	ds_write_b16 v6, v31 offset:2880
	v_add_f32_e32 v29, v29, v30
	v_mul_f32_e32 v31, v46, v32
	ds_swizzle_b32 v33, v29 offset:swizzle(SWAP,16)
	v_mul_f32_e32 v31, v17, v31
	v_mul_f32_e32 v30, v47, v32
	v_cvt_pk_bf16_f32 v31, v31, s0
	v_mul_f32_e32 v30, v16, v30
	ds_write_b16 v6, v31 offset:2944
	v_cvt_pk_bf16_f32 v44, v30, s0
	ds_read2_b32 v[30:31], v43 offset0:128 offset1:160
	s_waitcnt lgkmcnt(2)
	v_add_f32_e32 v29, v29, v33
	ds_read2_b32 v[32:33], v43 offset0:192 offset1:224
	v_fmamk_f32 v29, v29, 0x3c000000, v244
	v_rsq_f32_e32 v29, v29
	s_waitcnt lgkmcnt(1)
	v_sub_f32_e32 v40, v40, v31
	v_sub_f32_e32 v39, v39, v30
	v_mul_f32_e32 v30, v40, v40
	v_fmac_f32_e32 v30, v39, v39
	s_waitcnt lgkmcnt(0)
	v_sub_f32_e32 v38, v38, v32
	v_fmac_f32_e32 v30, v38, v38
	v_sub_f32_e32 v37, v37, v33
	v_fmac_f32_e32 v30, v37, v37
	s_nop 1
	v_mov_b32_dpp v31, v30 quad_perm:[1,0,3,2] row_mask:0xf bank_mask:0xf
	v_mul_f32_e32 v32, v50, v29
	v_mul_f32_e32 v32, v23, v32
	v_cvt_pk_bf16_f32 v32, v32, s0
	ds_write_b16 v6, v32 offset:4096
	v_add_f32_e32 v30, v30, v31
	s_nop 1
	v_mov_b32_dpp v31, v30 quad_perm:[2,3,0,1] row_mask:0xf bank_mask:0xf
	v_mul_f32_e32 v32, v51, v29
	v_mul_f32_e32 v32, v22, v32
	v_cvt_pk_bf16_f32 v32, v32, s0
	ds_write_b16 v6, v32 offset:4160
	v_add_f32_e32 v30, v30, v31
	s_nop 1
	v_mov_b32_dpp v31, v30 row_half_mirror row_mask:0xf bank_mask:0xf
	v_mul_f32_e32 v32, v42, v29
	v_add_u32_e32 v43, 0x2400, v15
	v_mul_f32_e32 v32, v17, v32
	v_cvt_pk_bf16_f32 v32, v32, s0
	v_add_f32_e32 v33, v30, v31
	s_nop 1
	v_mov_b32_dpp v42, v33 row_mirror row_mask:0xf bank_mask:0xf
	ds_read2_b32 v[30:31], v43 offset1:32
	ds_write_b16 v6, v32 offset:4224
	v_mul_f32_e32 v29, v41, v29
	v_mul_f32_e32 v29, v16, v29
	v_add_f32_e32 v41, v33, v42
	ds_read2_b32 v[32:33], v43 offset0:64 offset1:96
	s_waitcnt lgkmcnt(2)
	v_sub_f32_e32 v36, v36, v31
	v_sub_f32_e32 v35, v35, v30
	v_mul_f32_e32 v30, v36, v36
	v_fmac_f32_e32 v30, v35, v35
	s_waitcnt lgkmcnt(0)
	v_sub_f32_e32 v32, v34, v32
	v_fmac_f32_e32 v30, v32, v32
	v_sub_f32_e32 v33, v28, v33
	v_fmac_f32_e32 v30, v33, v33
	s_nop 1
	v_mov_b32_dpp v28, v30 quad_perm:[1,0,3,2] row_mask:0xf bank_mask:0xf
	ds_swizzle_b32 v42, v41 offset:swizzle(SWAP,16)
	v_cvt_pk_bf16_f32 v29, v29, s0
	ds_write_b16 v6, v29 offset:4288
	ds_write_b16 v6, v44 offset:3008
	v_add_f32_e32 v28, v30, v28
	s_nop 1
	v_mov_b32_dpp v30, v28 quad_perm:[2,3,0,1] row_mask:0xf bank_mask:0xf
	s_waitcnt lgkmcnt(2)
	v_add_f32_e32 v31, v41, v42
	v_fmamk_f32 v31, v31, 0x3c000000, v244
	v_rsq_f32_e32 v31, v31
	v_add_f32_e32 v28, v28, v30
	s_nop 1
	v_mov_b32_dpp v30, v28 row_half_mirror row_mask:0xf bank_mask:0xf
	v_mul_f32_e32 v29, v39, v31
	v_mul_f32_e32 v29, v23, v29
	v_cvt_pk_bf16_f32 v29, v29, s0
	ds_write_b16 v6, v29 offset:4352
	v_add_f32_e32 v28, v28, v30
	s_nop 1
	v_mov_b32_dpp v30, v28 row_mirror row_mask:0xf bank_mask:0xf
	v_mul_f32_e32 v29, v40, v31
	v_mul_f32_e32 v29, v22, v29
	v_cvt_pk_bf16_f32 v29, v29, s0
	ds_write_b16 v6, v29 offset:4416
	v_add_f32_e32 v30, v28, v30
	ds_swizzle_b32 v34, v30 offset:swizzle(SWAP,16)
	v_mul_f32_e32 v29, v38, v31
	v_mul_f32_e32 v29, v17, v29
	v_cvt_pk_bf16_f32 v28, v29, s0
	ds_write_b16 v6, v28 offset:4480
	ds_read2_b32 v[28:29], v43 offset0:128 offset1:160
	s_waitcnt lgkmcnt(2)
	v_add_f32_e32 v30, v30, v34
	v_fmamk_f32 v30, v30, 0x3c000000, v244
	v_mul_f32_e32 v37, v37, v31
	v_rsq_f32_e32 v34, v30
	ds_read2_b32 v[30:31], v43 offset0:192 offset1:224
	s_waitcnt lgkmcnt(1)
	v_sub_f32_e32 v29, v27, v29
	v_sub_f32_e32 v28, v26, v28
	v_mul_f32_e32 v26, v29, v29
	v_fmac_f32_e32 v26, v28, v28
	s_waitcnt lgkmcnt(0)
	v_sub_f32_e32 v30, v25, v30
	v_fmac_f32_e32 v26, v30, v30
	v_sub_f32_e32 v31, v24, v31
	v_fmac_f32_e32 v26, v31, v31
	s_nop 1
	v_mov_b32_dpp v24, v26 quad_perm:[1,0,3,2] row_mask:0xf bank_mask:0xf
	v_mul_f32_e32 v25, v16, v37
	v_cvt_pk_bf16_f32 v25, v25, s0
	ds_write_b16 v6, v25 offset:4544
	v_mul_f32_e32 v25, v35, v34
	v_add_f32_e32 v24, v26, v24
	s_nop 1
	v_mov_b32_dpp v26, v24 quad_perm:[2,3,0,1] row_mask:0xf bank_mask:0xf
	v_mul_f32_e32 v25, v23, v25
	v_cvt_pk_bf16_f32 v25, v25, s0
	ds_write_b16 v6, v25 offset:4608
	v_mul_f32_e32 v25, v36, v34
	v_add_f32_e32 v24, v24, v26
	s_nop 1
	v_mov_b32_dpp v26, v24 row_half_mirror row_mask:0xf bank_mask:0xf
	v_mul_f32_e32 v25, v22, v25
	v_cvt_pk_bf16_f32 v25, v25, s0
	ds_write_b16 v6, v25 offset:4672
	v_mul_f32_e32 v25, v32, v34
	v_add_f32_e32 v24, v24, v26
	s_nop 1
	v_mov_b32_dpp v26, v24 row_mirror row_mask:0xf bank_mask:0xf
	v_mul_f32_e32 v25, v17, v25
	v_cvt_pk_bf16_f32 v25, v25, s0
	ds_write_b16 v6, v25 offset:4736
	v_mul_f32_e32 v25, v33, v34
	v_add_f32_e32 v26, v24, v26
	ds_swizzle_b32 v27, v26 offset:swizzle(SWAP,16)
	v_mul_f32_e32 v24, v16, v25
	v_add_u32_e32 v33, 0x3000, v15
	v_cvt_pk_bf16_f32 v32, v24, s0
	ds_read2_b32 v[24:25], v33 offset1:32
	s_waitcnt lgkmcnt(1)
	v_add_f32_e32 v26, v26, v27
	v_fmamk_f32 v26, v26, 0x3c000000, v244
	v_rsq_f32_e32 v34, v26
	ds_read2_b32 v[26:27], v33 offset0:64 offset1:96
	s_waitcnt lgkmcnt(1)
	v_sub_f32_e32 v25, v21, v25
	v_sub_f32_e32 v24, v18, v24
	v_mul_f32_e32 v18, v25, v25
	v_fmac_f32_e32 v18, v24, v24
	s_waitcnt lgkmcnt(0)
	v_sub_f32_e32 v26, v20, v26
	v_fmac_f32_e32 v18, v26, v26
	v_sub_f32_e32 v27, v19, v27
	v_fmac_f32_e32 v18, v27, v27
	s_nop 1
	v_mov_b32_dpp v19, v18 quad_perm:[1,0,3,2] row_mask:0xf bank_mask:0xf
	v_mul_f32_e32 v20, v28, v34
	v_mul_f32_e32 v20, v23, v20
	v_cvt_pk_bf16_f32 v20, v20, s0
	ds_write_b16 v6, v20 offset:4864
	v_add_f32_e32 v18, v18, v19
	s_nop 1
	v_mov_b32_dpp v19, v18 quad_perm:[2,3,0,1] row_mask:0xf bank_mask:0xf
	v_mul_f32_e32 v20, v29, v34
	v_mul_f32_e32 v20, v22, v20
	v_cvt_pk_bf16_f32 v20, v20, s0
	ds_write_b16 v6, v20 offset:4928
	v_add_f32_e32 v18, v18, v19
	s_nop 1
	v_mov_b32_dpp v19, v18 row_half_mirror row_mask:0xf bank_mask:0xf
	v_mul_f32_e32 v20, v30, v34
	v_mul_f32_e32 v20, v17, v20
	v_cvt_pk_bf16_f32 v20, v20, s0
	ds_write_b16 v6, v20 offset:4992
	v_add_f32_e32 v21, v18, v19
	s_nop 1
	v_mov_b32_dpp v28, v21 row_mirror row_mask:0xf bank_mask:0xf
	ds_read2_b32 v[18:19], v33 offset0:128 offset1:160
	v_mul_f32_e32 v20, v31, v34
	v_mul_f32_e32 v29, v16, v20
	ds_write_b16 v6, v32 offset:4800
	v_add_f32_e32 v28, v21, v28
	ds_read2_b32 v[20:21], v33 offset0:192 offset1:224
	s_waitcnt lgkmcnt(2)
	v_sub_f32_e32 v11, v11, v18
	v_sub_f32_e32 v18, v14, v19
	v_mul_f32_e32 v14, v18, v18
	v_fmac_f32_e32 v14, v11, v11
	s_waitcnt lgkmcnt(0)
	v_sub_f32_e32 v19, v13, v20
	v_fmac_f32_e32 v14, v19, v19
	v_sub_f32_e32 v20, v12, v21
	v_fmac_f32_e32 v14, v20, v20
	s_nop 1
	v_mov_b32_dpp v12, v14 quad_perm:[1,0,3,2] row_mask:0xf bank_mask:0xf
	ds_swizzle_b32 v30, v28 offset:swizzle(SWAP,16)
	v_cvt_pk_bf16_f32 v13, v29, s0
	ds_write_b16 v6, v13 offset:5056
	v_add_f32_e32 v12, v14, v12
	s_nop 1
	v_mov_b32_dpp v14, v12 quad_perm:[2,3,0,1] row_mask:0xf bank_mask:0xf
	s_waitcnt lgkmcnt(1)
	v_add_f32_e32 v21, v28, v30
	v_fmamk_f32 v21, v21, 0x3c000000, v244
	v_rsq_f32_e32 v21, v21
	v_add_f32_e32 v12, v12, v14
	s_nop 1
	v_mov_b32_dpp v14, v12 row_half_mirror row_mask:0xf bank_mask:0xf
	v_mul_f32_e32 v13, v24, v21
	v_mul_f32_e32 v13, v23, v13
	v_cvt_pk_bf16_f32 v13, v13, s0
	ds_write_b16 v6, v13 offset:6144
	v_add_f32_e32 v12, v12, v14
	s_nop 1
	v_mov_b32_dpp v14, v12 row_mirror row_mask:0xf bank_mask:0xf
	v_mul_f32_e32 v13, v25, v21
	v_mul_f32_e32 v13, v22, v13
	v_cvt_pk_bf16_f32 v13, v13, s0
	ds_write_b16 v6, v13 offset:6208
	v_add_f32_e32 v14, v12, v14
	ds_swizzle_b32 v24, v14 offset:swizzle(SWAP,16)
	v_mul_f32_e32 v13, v26, v21
	v_mul_f32_e32 v13, v17, v13
	v_cvt_pk_bf16_f32 v13, v13, s0
	v_add_u32_e32 v25, 0x3400, v15
	ds_write_b16 v6, v13 offset:6272
	ds_read2_b32 v[12:13], v25 offset1:32
	s_waitcnt lgkmcnt(2)
	v_add_f32_e32 v14, v14, v24
	v_fmamk_f32 v14, v14, 0x3c000000, v244
	v_rsq_f32_e32 v24, v14
	ds_read2_b32 v[14:15], v25 offset0:64 offset1:96
	s_waitcnt lgkmcnt(1)
	v_sub_f32_e32 v7, v7, v12
	v_sub_f32_e32 v12, v10, v13
	v_mul_f32_e32 v10, v12, v12
	v_fmac_f32_e32 v10, v7, v7
	s_waitcnt lgkmcnt(0)
	v_sub_f32_e32 v13, v9, v14
	v_fmac_f32_e32 v10, v13, v13
	v_sub_f32_e32 v14, v8, v15
	v_fmac_f32_e32 v10, v14, v14
	s_nop 1
	v_mov_b32_dpp v8, v10 quad_perm:[1,0,3,2] row_mask:0xf bank_mask:0xf
	v_mul_f32_e32 v21, v27, v21
	v_mul_f32_e32 v9, v16, v21
	v_cvt_pk_bf16_f32 v9, v9, s0
	ds_write_b16 v6, v9 offset:6336
	v_add_f32_e32 v8, v10, v8
	s_nop 1
	v_mov_b32_dpp v10, v8 quad_perm:[2,3,0,1] row_mask:0xf bank_mask:0xf
	v_mul_f32_e32 v9, v11, v24
	v_mul_f32_e32 v9, v23, v9
	v_cvt_pk_bf16_f32 v9, v9, s0
	ds_write_b16 v6, v9 offset:6400
	v_add_f32_e32 v8, v8, v10
	s_nop 1
	v_mov_b32_dpp v10, v8 row_half_mirror row_mask:0xf bank_mask:0xf
	v_mul_f32_e32 v9, v18, v24
	v_mul_f32_e32 v9, v22, v9
	v_cvt_pk_bf16_f32 v9, v9, s0
	ds_write_b16 v6, v9 offset:6464
	v_add_f32_e32 v10, v8, v10
	s_nop 1
	v_mov_b32_dpp v11, v10 row_mirror row_mask:0xf bank_mask:0xf
	v_mul_f32_e32 v9, v19, v24
	v_mul_f32_e32 v8, v17, v9
	v_cvt_pk_bf16_f32 v15, v8, s0
	ds_read2_b32 v[8:9], v25 offset0:128 offset1:160
	ds_write_b16 v6, v15 offset:6528
	v_add_f32_e32 v15, v10, v11
	ds_read2_b32 v[10:11], v25 offset0:192 offset1:224
	ds_swizzle_b32 v18, v15 offset:swizzle(SWAP,16)
	s_waitcnt lgkmcnt(3)
	v_sub_f32_e32 v5, v5, v9
	v_sub_f32_e32 v4, v4, v8
	v_mul_f32_e32 v8, v5, v5
	v_fmac_f32_e32 v8, v4, v4
	s_waitcnt lgkmcnt(1)
	v_sub_f32_e32 v3, v3, v10
	v_fmac_f32_e32 v8, v3, v3
	v_sub_f32_e32 v2, v2, v11
	v_fmac_f32_e32 v8, v2, v2
	s_nop 1
	v_mov_b32_dpp v9, v8 quad_perm:[1,0,3,2] row_mask:0xf bank_mask:0xf
	s_waitcnt lgkmcnt(0)
	v_add_f32_e32 v11, v15, v18
	v_fmamk_f32 v11, v11, 0x3c000000, v244
	v_rsq_f32_e32 v11, v11
	v_mul_f32_e32 v10, v20, v24
	v_add_f32_e32 v8, v8, v9
	s_nop 1
	v_mov_b32_dpp v9, v8 quad_perm:[2,3,0,1] row_mask:0xf bank_mask:0xf
	v_mul_f32_e32 v7, v7, v11
	v_mul_f32_e32 v7, v23, v7
	v_cvt_pk_bf16_f32 v7, v7, s0
	ds_write_b16 v6, v7 offset:6656
	v_add_f32_e32 v8, v8, v9
	s_nop 1
	v_mov_b32_dpp v9, v8 row_half_mirror row_mask:0xf bank_mask:0xf
	v_mul_f32_e32 v7, v12, v11
	v_mul_f32_e32 v7, v22, v7
	v_cvt_pk_bf16_f32 v7, v7, s0
	ds_write_b16 v6, v7 offset:6720
	v_add_f32_e32 v8, v8, v9
	s_nop 1
	v_mov_b32_dpp v9, v8 row_mirror row_mask:0xf bank_mask:0xf
	v_mul_f32_e32 v7, v13, v11
	v_mul_f32_e32 v7, v17, v7
	v_cvt_pk_bf16_f32 v7, v7, s0
	ds_write_b16 v6, v7 offset:6784
	v_add_f32_e32 v8, v8, v9
	ds_swizzle_b32 v9, v8 offset:swizzle(SWAP,16)
	v_mul_f32_e32 v7, v14, v11
	v_mul_f32_e32 v10, v16, v10
	v_mul_f32_e32 v7, v16, v7
	v_cvt_pk_bf16_f32 v10, v10, s0
	s_waitcnt lgkmcnt(0)
	v_add_f32_e32 v8, v8, v9
	v_fmamk_f32 v8, v8, 0x3c000000, v244
	v_rsq_f32_e32 v8, v8
	v_cvt_pk_bf16_f32 v7, v7, s0
	ds_write_b16 v6, v10 offset:6592
	ds_write_b16 v6, v7 offset:6848
	v_mul_f32_e32 v4, v4, v8
	v_mul_f32_e32 v4, v23, v4
	v_mul_f32_e32 v2, v2, v8
	v_cvt_pk_bf16_f32 v4, v4, s0
	v_mul_f32_e32 v2, v16, v2
	ds_write_b16 v6, v4 offset:6912
	v_mul_f32_e32 v4, v5, v8
	v_mul_f32_e32 v3, v3, v8
	v_cvt_pk_bf16_f32 v2, v2, s0
	v_mul_f32_e32 v4, v22, v4
	v_mul_f32_e32 v3, v17, v3
	ds_write_b16 v6, v2 offset:7104
	v_lshlrev_b32_e32 v2, 4, v66
	v_cvt_pk_bf16_f32 v4, v4, s0
	v_cvt_pk_bf16_f32 v3, v3, s0
	v_and_b32_e32 v2, 0xf0, v2
	ds_write_b16 v6, v4 offset:6976
	ds_write_b16 v6, v3 offset:7040
	v_ashrrev_i32_e32 v10, 4, v66
	v_add_u32_e32 v18, s0, v2
	v_mov_b32_e32 v3, v231
	s_waitcnt lgkmcnt(0)
	v_lshl_add_u64 v[12:13], s[4:5], 0, v[2:3]
	v_lshl_add_u32 v2, v10, 8, v18
	v_ashrrev_i32_e32 v11, 31, v10
	ds_read_b128 v[2:5], v2
	v_lshlrev_b64 v[6:7], 11, v[10:11]
	v_add_u32_e32 v16, 4, v10
	v_lshl_add_u64 v[14:15], v[12:13], 0, v[6:7]
	v_lshl_add_u32 v6, v16, 8, v18
	ds_read_b128 v[6:9], v6
	v_ashrrev_i32_e32 v17, 31, v16
	s_waitcnt lgkmcnt(1)
	global_store_dwordx4 v[14:15], v[2:5], off offset:1024
	s_nop 1
	v_lshlrev_b64 v[2:3], 11, v[16:17]
	v_lshl_add_u64 v[2:3], v[12:13], 0, v[2:3]
	s_waitcnt lgkmcnt(0)
	global_store_dwordx4 v[2:3], v[6:9], off offset:1024
	v_add_u32_e32 v16, 12, v10
	v_ashrrev_i32_e32 v17, 31, v16
	v_add_u32_e32 v6, 8, v10
	v_lshl_add_u32 v2, v6, 8, v18
	v_ashrrev_i32_e32 v7, 31, v6
	ds_read_b128 v[2:5], v2
	v_lshlrev_b64 v[6:7], 11, v[6:7]
	v_lshl_add_u64 v[14:15], v[12:13], 0, v[6:7]
	v_lshl_add_u32 v6, v16, 8, v18
	ds_read_b128 v[6:9], v6
	s_waitcnt lgkmcnt(1)
	global_store_dwordx4 v[14:15], v[2:5], off offset:1024
	s_nop 1
	v_lshlrev_b64 v[2:3], 11, v[16:17]
	v_lshl_add_u64 v[2:3], v[12:13], 0, v[2:3]
	s_waitcnt lgkmcnt(0)
	global_store_dwordx4 v[2:3], v[6:9], off offset:1024
	v_add_u32_e32 v16, 20, v10
	v_ashrrev_i32_e32 v17, 31, v16
	v_add_u32_e32 v6, 16, v10
	v_lshl_add_u32 v2, v6, 8, v18
	v_ashrrev_i32_e32 v7, 31, v6
	ds_read_b128 v[2:5], v2
	v_lshlrev_b64 v[6:7], 11, v[6:7]
	v_lshl_add_u64 v[14:15], v[12:13], 0, v[6:7]
	v_lshl_add_u32 v6, v16, 8, v18
	ds_read_b128 v[6:9], v6
	s_waitcnt lgkmcnt(1)
	global_store_dwordx4 v[14:15], v[2:5], off offset:1024
	s_nop 1
	v_lshlrev_b64 v[2:3], 11, v[16:17]
	v_lshl_add_u64 v[2:3], v[12:13], 0, v[2:3]
	s_waitcnt lgkmcnt(0)
	global_store_dwordx4 v[2:3], v[6:9], off offset:1024
	s_nop 1
	v_add_u32_e32 v6, 24, v10
	v_lshl_add_u32 v2, v6, 8, v18
	v_ashrrev_i32_e32 v7, 31, v6
	ds_read_b128 v[2:5], v2
	v_lshlrev_b64 v[6:7], 11, v[6:7]
	v_add_u32_e32 v10, 28, v10
	v_lshl_add_u64 v[14:15], v[12:13], 0, v[6:7]
	v_lshl_add_u32 v6, v10, 8, v18
	ds_read_b128 v[6:9], v6
	v_ashrrev_i32_e32 v11, 31, v10
	s_waitcnt lgkmcnt(1)
	global_store_dwordx4 v[14:15], v[2:5], off offset:1024
	s_nop 1
	v_lshlrev_b64 v[2:3], 11, v[10:11]
	v_lshl_add_u64 v[2:3], v[12:13], 0, v[2:3]
	s_waitcnt lgkmcnt(0)
	global_store_dwordx4 v[2:3], v[6:9], off offset:1024
